# merge n-loop: k-step 1 loads issued with k-step 0 (second register set), k-step 2 loads one stage earlier
# baseline (speedup 1.0000x reference)
; #define GLOAD(ko) do { \
;     _Pragma("unroll") for (int i = 0; i < 4; ++i) ra[i] = *(const u32x4*)(ap + (size_t)(32 * i) * lda + (ko)); \
;     _Pragma("unroll") for (int i = 0; i < NB; ++i) rb[i] = *(const u32x4*)(bp + (size_t)(bstride * i) * ldb + (ko)); } while (0)
; #define GSTORE(st) do { \
;     _Pragma("unroll") for (int i = 0; i < 4; ++i) *(u32x4*)(sA + (st) * GST + so + 32 * i * 64) = ra[i]; \
;     _Pragma("unroll") for (int i = 0; i < NB; ++i) *(u32x4*)(sB + (st) * GST + so + 32 * i * 64) = rb[i]; } while (0)
;     ...
;   __syncthreads();
;   GLOAD(0); GSTORE(0);
;   if (nk > 1) GLOAD(64);
;   __syncthreads();
;   for (int kt = 0; kt < nk; ++kt) {
;     const int cur = kt & 1;
;     if (kt + 1 < nk) { GSTORE(cur ^ 1); if (kt + 2 < nk) GLOAD((kt + 2) * 64); }
; DI void merge_tile(const Params& p, int l, int tile, char* smem) {
;     ...
; #pragma unroll 1
;   for (int n = 0; n < 4; ++n) {
;     f32x4 accB[4][2]; zero_acc<2>(accB);
;     gemm_mainloop<2>(accB, P_PROJ + (size_t)mt * 128 * PW + C_GATE + n * 256, PW, P_WBT + ((size_t)(l * 4 + n) * 1024 + nt * 64) * 256, 256, 256, sA, sB);
.LBB0_47:
	v_mov_b32_e32 v154, v111
	v_mov_b32_e32 v111, v164
	v_mov_b32_e32 v164, v88
	v_mov_b32_e32 v88, v183
	v_mov_b32_e32 v183, v97
	v_mov_b32_e32 v186, v106
	v_mov_b32_e32 v97, v213
	v_mov_b32_e32 v106, v214
	v_cvt_pk_bf16_f32 v214, v0, v158
	v_cvt_pk_bf16_f32 v213, v160, v161
	v_cvt_pk_bf16_f32 v160, v26, v27
	v_mov_b32 v26, v188
	s_add_u32 s12, s58, s22
	v_lshrrev_b32_e32 v0, 3, v26
	v_lshlrev_b32_e32 v4, 4, v26
	v_mul_u32_u24_e32 v2, 0x2600, v0
	v_and_b32_e32 v20, 0x70, v4
	v_mul_hi_u32_u24_e32 v3, 0x2600, v0
	v_or_b32_e32 v2, v2, v20
	s_addc_u32 s13, s59, s23
	v_lshl_add_u64 v[14:15], s[12:13], 0, v[2:3]
	v_add_co_u32_e32 v34, vcc, s11, v14
	s_mov_b32 s7, 0x6cf1000
	s_nop 0
	v_addc_co_u32_e32 v35, vcc, 0, v15, vcc
	v_add_co_u32_e32 v36, vcc, s7, v14
	s_mov_b32 s7, 0x6d3d000
	s_nop 0
	v_addc_co_u32_e32 v37, vcc, 0, v15, vcc
	v_mov_b32_e32 v157, v112
	v_mov_b32_e32 v112, v163
	v_mov_b32_e32 v163, v89
	v_mov_b32_e32 v89, v184
	v_mov_b32_e32 v184, v96
	v_mov_b32_e32 v96, v212
	v_cvt_pk_bf16_f32 v212, v171, v172
	v_cvt_pk_bf16_f32 v171, v70, v71
	v_add_co_u32_e32 v70, vcc, s7, v14
	v_lshlrev_b64 v[18:19], 9, v[0:1]
	s_nop 0
	v_addc_co_u32_e32 v71, vcc, 0, v15, vcc
	s_mov_b32 s7, 0x6d89000
	s_add_u32 s12, s58, s0
	v_mov_b32_e32 v155, v110
	v_mov_b32_e32 v110, v159
	v_mov_b32_e32 v159, v87
	v_mov_b32_e32 v87, v182
	v_mov_b32_e32 v182, v94
	v_mov_b32_e32 v94, v210
	v_cvt_pk_bf16_f32 v210, v169, v170
	v_cvt_pk_bf16_f32 v170, v72, v73
	v_add_co_u32_e32 v72, vcc, s7, v14
	v_or_b32_e32 v18, v18, v20
	s_addc_u32 s13, s59, s1
	s_barrier
	global_load_dwordx4 v[2:5], v[34:35], off offset:2560
	global_load_dwordx4 v[6:9], v[36:37], off offset:2560
	v_addc_co_u32_e32 v73, vcc, 0, v15, vcc
	v_lshl_add_u64 v[22:23], s[12:13], 0, v[18:19]
	s_mov_b32 s7, 0x2700000
	v_mov_b32_e32 v152, v121
	v_mov_b32_e32 v121, v167
	v_mov_b32_e32 v167, v78
	v_mov_b32_e32 v78, v74
	v_add_co_u32_e32 v74, vcc, s7, v22
	v_mov_b32_e32 v150, v119
	v_mov_b32_e32 v119, v178
	v_mov_b32_e32 v178, v80
	v_mov_b32_e32 v80, v75
	global_load_dwordx4 v[10:13], v[70:71], off offset:2560
	global_load_dwordx4 v[14:17], v[72:73], off offset:2560
	v_addc_co_u32_e32 v75, vcc, 0, v23, vcc
	s_mov_b32 s7, 0x2704000
	v_mov_b32_e32 v151, v118
	v_mov_b32_e32 v118, v177
	v_mov_b32_e32 v177, v81
	v_mov_b32_e32 v81, v76
	v_add_co_u32_e32 v76, vcc, s7, v22
	v_cvt_pk_bf16_f32 v169, v77, v207
	global_load_dwordx4 v[18:21], v[74:75], off
	v_addc_co_u32_e32 v77, vcc, 0, v23, vcc
	global_load_dwordx4 v[22:25], v[76:77], off
	global_load_dwordx4 v[218:221], v[34:35], off offset:2688
	global_load_dwordx4 v[222:225], v[36:37], off offset:2688
	global_load_dwordx4 v[226:229], v[70:71], off offset:2688
	global_load_dwordx4 v[230:233], v[72:73], off offset:2688
	global_load_dwordx4 v[234:237], v[74:75], off offset:128
	global_load_dwordx4 v[238:241], v[76:77], off offset:128
	v_lshrrev_b32_e32 v27, 4, v26
	v_cvt_pk_bf16_f32 v158, v28, v29
	v_xor_b32_e32 v28, v27, v26
	v_lshlrev_b32_e32 v28, 4, v28
	v_and_b32_e32 v28, 0x70, v28
	v_lshl_or_b32 v0, v0, 7, v28
	s_waitcnt vmcnt(11)
	ds_write_b128 v0, v[2:5]
	s_waitcnt vmcnt(10)
	ds_write_b128 v0, v[6:9] offset:4096
	s_waitcnt vmcnt(9)
	ds_write_b128 v0, v[10:13] offset:8192
	s_waitcnt vmcnt(8)
	ds_write_b128 v0, v[14:17] offset:12288
	s_waitcnt vmcnt(7)
	ds_write_b128 v0, v[18:21] offset:32768
	s_waitcnt vmcnt(6)
	ds_write_b128 v0, v[22:25] offset:36864
	global_load_dwordx4 v[2:5], v[34:35], off offset:2816
	global_load_dwordx4 v[6:9], v[36:37], off offset:2816
	global_load_dwordx4 v[10:13], v[70:71], off offset:2816
	global_load_dwordx4 v[14:17], v[72:73], off offset:2816
	global_load_dwordx4 v[18:21], v[74:75], off offset:256
	global_load_dwordx4 v[22:25], v[76:77], off offset:256
	s_waitcnt lgkmcnt(0)
	s_barrier
	s_waitcnt vmcnt(11)
	ds_write_b128 v0, v[218:221] offset:16384
	s_waitcnt vmcnt(10)
	ds_write_b128 v0, v[222:225] offset:20480
	s_waitcnt vmcnt(9)
	ds_write_b128 v0, v[226:229] offset:24576
	s_waitcnt vmcnt(8)
	ds_write_b128 v0, v[230:233] offset:28672
	s_waitcnt vmcnt(7)
	ds_write_b128 v0, v[234:237] offset:49152
	s_waitcnt vmcnt(6)
	ds_write_b128 v0, v[238:241] offset:53248
	v_cvt_pk_bf16_f32 v172, v179, v180
	v_and_b32_e32 v29, 15, v26
	v_bfe_u32 v179, v26, 4, 2
	v_bfe_u32 v180, v26, 1, 3
	v_lshrrev_b32_e32 v26, 1, v26
	v_cvt_pk_bf16_f32 v174, v173, v174
	v_cvt_pk_bf16_f32 v173, v175, v176
	v_and_or_b32 v28, v26, 64, v29
	v_and_or_b32 v176, v26, 32, v29
	v_bitop3_b32 v26, v27, v180, 3 bitop3:0x6c
	v_lshlrev_b32_e32 v190, 4, v26
	v_lshlrev_b32_e32 v191, 7, v28
	v_lshlrev_b32_e32 v192, 7, v176
	v_or_b32_e32 v175, v190, v191
	v_or_b32_e32 v176, v190, v192
	v_mov_b32_e32 v153, v120
	v_mov_b32_e32 v120, v162
	v_mov_b32_e32 v162, v86
	v_mov_b32_e32 v86, v181
	v_mov_b32_e32 v181, v95
	v_mov_b32_e32 v187, v109
	v_mov_b32_e32 v206, v108
	v_mov_b32_e32 v95, v211
	v_mov_b32_e32 v109, v217
	v_mov_b32_e32 v108, v216
	v_cvt_pk_bf16_f32 v211, v165, v168
	v_cvt_pk_bf16_f32 v161, v32, v33
	v_cvt_pk_bf16_f32 v165, v30, v31
	ds_read_b128 v[26:29], v175
	ds_read_b128 v[30:33], v175 offset:2048
	ds_read_b128 v[194:197], v175 offset:4096
	ds_read_b128 v[216:219], v175 offset:6144
	ds_read_b128 v[220:223], v176 offset:32768
	ds_read_b128 v[224:227], v176 offset:34816
	v_bitop3_b32 v179, v179, v180, 4 bitop3:0x36
	v_lshlrev_b32_e32 v179, 4, v179
	v_or_b32_e32 v180, v179, v191
	v_or_b32_e32 v179, v179, v192
	s_waitcnt lgkmcnt(1)
	v_mfma_f32_16x16x32_bf16 v[228:231], v[220:223], v[26:29], 0
	v_cvt_pk_bf16_f32 v168, v208, v209
	s_add_u32 s0, s0, 0x80000
	s_addc_u32 s1, s1, 0
	s_waitcnt lgkmcnt(0)
	v_mfma_f32_16x16x32_bf16 v[26:29], v[224:227], v[26:29], 0
	s_add_i32 s6, s6, -1
	s_add_u32 s22, s22, 0x200
	v_mov_b32_e32 v156, v113
	v_mfma_f32_16x16x32_bf16 v[232:235], v[220:223], v[30:33], 0
	v_mov_b32_e32 v113, v166
	v_mov_b32_e32 v166, v79
	v_mov_b32_e32 v79, v185
	v_mfma_f32_16x16x32_bf16 v[30:33], v[224:227], v[30:33], 0
	v_mov_b32_e32 v185, v107
	s_addc_u32 s23, s23, 0
	v_mov_b32_e32 v107, v215
	v_mfma_f32_16x16x32_bf16 v[236:239], v[220:223], v[194:197], 0
	s_cmp_lg_u32 s6, 0
	v_mov_b32_e32 v215, v123
	v_mov_b32_e32 v208, v206
	v_mfma_f32_16x16x32_bf16 v[194:197], v[224:227], v[194:197], 0
	v_mov_b32_e32 v209, v187
	v_mov_b32_e32 v207, v185
	v_mov_b32_e32 v185, v91
	v_mfma_f32_16x16x32_bf16 v[220:223], v[220:223], v[216:219], 0
	v_mfma_f32_16x16x32_bf16 v[216:219], v[224:227], v[216:219], 0
	ds_read_b128 v[224:227], v180
	ds_read_b128 v[240:243], v180 offset:2048
	ds_read_b128 v[244:247], v180 offset:4096
	ds_read_b128 v[248:251], v180 offset:6144
	ds_read_b128 v[190:193], v179 offset:32768
	ds_read_b128 v[198:201], v179 offset:34816
	s_waitcnt lgkmcnt(0)
	s_barrier
; #define GLOAD(ko) do { \
;     _Pragma("unroll") for (int i = 0; i < 4; ++i) ra[i] = *(const u32x4*)(ap + (size_t)(32 * i) * lda + (ko)); \
;     _Pragma("unroll") for (int i = 0; i < NB; ++i) rb[i] = *(const u32x4*)(bp + (size_t)(bstride * i) * ldb + (ko)); } while (0)
; #define GSTORE(st) do { \
;     _Pragma("unroll") for (int i = 0; i < 4; ++i) *(u32x4*)(sA + (st) * GST + so + 32 * i * 64) = ra[i]; \
;     _Pragma("unroll") for (int i = 0; i < NB; ++i) *(u32x4*)(sB + (st) * GST + so + 32 * i * 64) = rb[i]; } while (0)
;     ...
;   for (int kt = 0; kt < nk; ++kt) {
;     const int cur = kt & 1;
;     if (kt + 1 < nk) { GSTORE(cur ^ 1); if (kt + 2 < nk) GLOAD((kt + 2) * 64); }
;     if (LOWREG) {
;       const bf16_t* cA = sA + cur * GST; const bf16_t* cB = sB + cur * GST;
; #pragma nounroll
;       for (int ks = 0; ks < 2; ++ks) {
;         bf16x8 af[4], bfr[NT];
; #pragma unroll
;         for (int mi = 0; mi < 4; ++mi) af[mi] = *(const bf16x8*)(cA + (wm * 64 + mi * 16 + fr) * 64 + (((ks * 4 + fq) ^ fsw) * 8));
; #pragma unroll
;         for (int ni = 0; ni < NT; ++ni) bfr[ni] = *(const bf16x8*)(cB + (wn * NT * 16 + ni * 16 + fr) * 64 + (((ks * 4 + fq) ^ fsw) * 8));
; #pragma unroll
;         for (int mi = 0; mi < 4; ++mi)
; #pragma unroll
;           for (int ni = 0; ni < NT; ++ni) acc[mi][ni] = __builtin_amdgcn_mfma_f32_16x16x32_bf16(bfr[ni], af[mi], acc[mi][ni], 0, 0, 0);
;       }
;     } else GCOMPUTE(cur);
;     __syncthreads();
	s_waitcnt vmcnt(5)
	ds_write_b128 v0, v[2:5]
	s_waitcnt vmcnt(4)
	ds_write_b128 v0, v[6:9] offset:4096
	s_waitcnt vmcnt(3)
	ds_write_b128 v0, v[10:13] offset:8192
	s_waitcnt vmcnt(2)
	ds_write_b128 v0, v[14:17] offset:12288
	s_waitcnt vmcnt(1)
	ds_write_b128 v0, v[18:21] offset:32768
	s_waitcnt vmcnt(0)
	ds_write_b128 v0, v[22:25] offset:36864
	global_load_dwordx4 v[2:5], v[34:35], off offset:2944
	global_load_dwordx4 v[6:9], v[36:37], off offset:2944
	global_load_dwordx4 v[10:13], v[70:71], off offset:2944
	global_load_dwordx4 v[14:17], v[72:73], off offset:2944
	global_load_dwordx4 v[18:21], v[74:75], off offset:384
	global_load_dwordx4 v[22:25], v[76:77], off offset:384
	v_mfma_f32_16x16x32_bf16 v[228:231], v[190:193], v[224:227], v[228:231]
	v_mfma_f32_16x16x32_bf16 v[224:227], v[198:201], v[224:227], v[26:29]
	v_mfma_f32_16x16x32_bf16 v[232:235], v[190:193], v[240:243], v[232:235]
	v_mfma_f32_16x16x32_bf16 v[240:243], v[198:201], v[240:243], v[30:33]
	v_mfma_f32_16x16x32_bf16 v[236:239], v[190:193], v[244:247], v[236:239]
	v_mfma_f32_16x16x32_bf16 v[194:197], v[198:201], v[244:247], v[194:197]
	v_mfma_f32_16x16x32_bf16 v[26:29], v[190:193], v[248:251], v[220:223]
	v_mfma_f32_16x16x32_bf16 v[30:33], v[198:201], v[248:251], v[216:219]
	ds_read_b128 v[70:73], v175 offset:16384
	ds_read_b128 v[74:77], v175 offset:18432
	ds_read_b128 v[190:193], v175 offset:20480
	ds_read_b128 v[34:37], v175 offset:22528
	ds_read_b128 v[198:201], v176 offset:49152
	ds_read_b128 v[216:219], v176 offset:51200
	s_waitcnt lgkmcnt(1)
	v_mfma_f32_16x16x32_bf16 v[220:223], v[198:201], v[70:73], v[228:231]
	s_waitcnt lgkmcnt(0)
	v_mfma_f32_16x16x32_bf16 v[70:73], v[216:219], v[70:73], v[224:227]
	v_mfma_f32_16x16x32_bf16 v[224:227], v[198:201], v[74:77], v[232:235]
	v_mfma_f32_16x16x32_bf16 v[74:77], v[216:219], v[74:77], v[240:243]
	v_mfma_f32_16x16x32_bf16 v[228:231], v[198:201], v[190:193], v[236:239]
	v_mfma_f32_16x16x32_bf16 v[190:193], v[216:219], v[190:193], v[194:197]
	v_mfma_f32_16x16x32_bf16 v[26:29], v[198:201], v[34:37], v[26:29]
	v_mfma_f32_16x16x32_bf16 v[30:33], v[216:219], v[34:37], v[30:33]
	ds_read_b128 v[34:37], v180 offset:16384
	ds_read_b128 v[194:197], v180 offset:18432
	ds_read_b128 v[198:201], v180 offset:20480
	ds_read_b128 v[216:219], v180 offset:22528
	ds_read_b128 v[232:235], v179 offset:49152
	ds_read_b128 v[236:239], v179 offset:51200
	s_waitcnt lgkmcnt(0)
	s_barrier
	s_waitcnt vmcnt(5)
	ds_write_b128 v0, v[2:5] offset:16384
	s_waitcnt vmcnt(4)
	ds_write_b128 v0, v[6:9] offset:20480
	s_waitcnt vmcnt(3)
	ds_write_b128 v0, v[10:13] offset:24576
	s_waitcnt vmcnt(2)
	ds_write_b128 v0, v[14:17] offset:28672
	s_waitcnt vmcnt(1)
	ds_write_b128 v0, v[18:21] offset:49152
	s_waitcnt vmcnt(0)
	ds_write_b128 v0, v[22:25] offset:53248
	ds_read_b128 v[2:5], v175
	ds_read_b128 v[6:9], v175 offset:2048
	ds_read_b128 v[10:13], v175 offset:4096
	ds_read_b128 v[14:17], v175 offset:6144
	ds_read_b128 v[18:21], v176 offset:32768
	ds_read_b128 v[22:25], v176 offset:34816
	v_mfma_f32_16x16x32_bf16 v[220:223], v[232:235], v[34:37], v[220:223]
	v_mov_b32_e32 v0, v151
	v_mfma_f32_16x16x32_bf16 v[34:37], v[236:239], v[34:37], v[70:73]
	v_mfma_f32_16x16x32_bf16 v[70:73], v[232:235], v[194:197], v[224:227]
	v_mfma_f32_16x16x32_bf16 v[74:77], v[236:239], v[194:197], v[74:77]
	v_mfma_f32_16x16x32_bf16 v[194:197], v[232:235], v[198:201], v[228:231]
	v_mfma_f32_16x16x32_bf16 v[190:193], v[236:239], v[198:201], v[190:193]
	v_mfma_f32_16x16x32_bf16 v[26:29], v[232:235], v[216:219], v[26:29]
	v_mfma_f32_16x16x32_bf16 v[30:33], v[236:239], v[216:219], v[30:33]
	v_mov_b32_e32 v216, v124
	v_mov_b32_e32 v217, v125
	s_waitcnt lgkmcnt(1)
	v_mfma_f32_16x16x32_bf16 v[198:201], v[18:21], v[2:5], v[220:223]
	s_waitcnt lgkmcnt(0)
	v_mfma_f32_16x16x32_bf16 v[2:5], v[22:25], v[2:5], v[34:37]
	v_mfma_f32_16x16x32_bf16 v[34:37], v[18:21], v[6:9], v[70:73]
	v_mfma_f32_16x16x32_bf16 v[6:9], v[22:25], v[6:9], v[74:77]
	v_mfma_f32_16x16x32_bf16 v[70:73], v[18:21], v[10:13], v[194:197]
	v_mfma_f32_16x16x32_bf16 v[10:13], v[22:25], v[10:13], v[190:193]
	v_mfma_f32_16x16x32_bf16 v[18:21], v[18:21], v[14:17], v[26:29]
	v_mfma_f32_16x16x32_bf16 v[14:17], v[22:25], v[14:17], v[30:33]
	ds_read_b128 v[22:25], v180
	s_nop 0
	ds_read_b128 v[26:29], v180 offset:2048
	ds_read_b128 v[30:33], v180 offset:4096
	ds_read_b128 v[74:77], v180 offset:6144
	ds_read_b128 v[190:193], v179 offset:32768
	ds_read_b128 v[194:197], v179 offset:34816
	s_waitcnt lgkmcnt(0)
	s_barrier
; #define BLO(u) __uint_as_float((u) << 16)
; #define BHI(u) __uint_as_float((u) & 0xffff0000u)
;     ...
;       for (int ks = 0; ks < 2; ++ks) {
;         bf16x8 af[4], bfr[NT];
; #pragma unroll
;         for (int mi = 0; mi < 4; ++mi) af[mi] = *(const bf16x8*)(cA + (wm * 64 + mi * 16 + fr) * 64 + (((ks * 4 + fq) ^ fsw) * 8));
; #pragma unroll
;         for (int ni = 0; ni < NT; ++ni) bfr[ni] = *(const bf16x8*)(cB + (wn * NT * 16 + ni * 16 + fr) * 64 + (((ks * 4 + fq) ^ fsw) * 8));
; #pragma unroll
;         for (int mi = 0; mi < 4; ++mi)
; #pragma unroll
;           for (int ni = 0; ni < NT; ++ni) acc[mi][ni] = __builtin_amdgcn_mfma_f32_16x16x32_bf16(bfr[ni], af[mi], acc[mi][ni], 0, 0, 0);
; DI void merge_tile(const Params& p, int l, int tile, char* smem) {
;     ...
; #pragma unroll
;     for (int mi = 0; mi < 4; ++mi)
; #pragma unroll
;       for (int ni = 0; ni < 2; ++ni) {
;         accM[mi][ni][0] += accB[mi][ni][0] * BLO(sg[mi][ni][0]); accM[mi][ni][1] += accB[mi][ni][1] * BHI(sg[mi][ni][0]);
;         accM[mi][ni][2] += accB[mi][ni][2] * BLO(sg[mi][ni][1]); accM[mi][ni][3] += accB[mi][ni][3] * BHI(sg[mi][ni][1]);
;       }
; #pragma unroll
;     for (int mi = 0; mi < 4; ++mi)
; #pragma unroll
;       for (int k = 0; k < 6; ++k) { sg[mi][k][0] = sg[mi][k + 2][0]; sg[mi][k][1] = sg[mi][k + 2][1]; }
	v_mfma_f32_16x16x32_bf16 v[198:201], v[190:193], v[22:25], v[198:201]
	v_mfma_f32_16x16x32_bf16 v[2:5], v[194:197], v[22:25], v[2:5]
	v_mfma_f32_16x16x32_bf16 v[22:25], v[190:193], v[26:29], v[34:37]
	v_mfma_f32_16x16x32_bf16 v[6:9], v[194:197], v[26:29], v[6:9]
	v_mfma_f32_16x16x32_bf16 v[26:29], v[190:193], v[30:33], v[70:73]
	v_mfma_f32_16x16x32_bf16 v[10:13], v[194:197], v[30:33], v[10:13]
	v_mfma_f32_16x16x32_bf16 v[18:21], v[190:193], v[74:77], v[18:21]
	v_mfma_f32_16x16x32_bf16 v[14:17], v[194:197], v[74:77], v[14:17]
	ds_read_b128 v[30:33], v175 offset:16384
	ds_read_b128 v[34:37], v175 offset:18432
	ds_read_b128 v[70:73], v175 offset:20480
	ds_read_b128 v[74:77], v175 offset:22528
	ds_read_b128 v[190:193], v176 offset:49152
	ds_read_b128 v[194:197], v176 offset:51200
	v_mov_b32_e32 v175, v167
	v_mov_b32_e32 v176, v166
	s_waitcnt lgkmcnt(1)
	v_mfma_f32_16x16x32_bf16 v[198:201], v[190:193], v[30:33], v[198:201]
	v_mov_b32_e32 v166, v101
	v_mov_b32_e32 v167, v105
	s_waitcnt lgkmcnt(0)
	v_mfma_f32_16x16x32_bf16 v[2:5], v[194:197], v[30:33], v[2:5]
	v_mfma_f32_16x16x32_bf16 v[22:25], v[190:193], v[34:37], v[22:25]
	v_mfma_f32_16x16x32_bf16 v[6:9], v[194:197], v[34:37], v[6:9]
	v_mfma_f32_16x16x32_bf16 v[26:29], v[190:193], v[70:73], v[26:29]
	v_mfma_f32_16x16x32_bf16 v[10:13], v[194:197], v[70:73], v[10:13]
	v_mfma_f32_16x16x32_bf16 v[18:21], v[190:193], v[74:77], v[18:21]
	v_mfma_f32_16x16x32_bf16 v[14:17], v[194:197], v[74:77], v[14:17]
	ds_read_b128 v[30:33], v180 offset:16384
	ds_read_b128 v[34:37], v180 offset:18432
	ds_read_b128 v[70:73], v180 offset:20480
	ds_read_b128 v[74:77], v180 offset:22528
	ds_read_b128 v[190:193], v179 offset:49152
	ds_read_b128 v[194:197], v179 offset:51200
	v_mov_b32_e32 v179, v178
	v_mov_b32_e32 v180, v177
	s_waitcnt lgkmcnt(1)
	v_mfma_f32_16x16x32_bf16 v[198:201], v[190:193], v[30:33], v[198:201]
	v_mov_b32_e32 v177, v102
	v_mov_b32_e32 v178, v103
	s_waitcnt lgkmcnt(0)
	v_mfma_f32_16x16x32_bf16 v[2:5], v[194:197], v[30:33], v[2:5]
	v_lshlrev_b32_e32 v30, 16, v214
	v_and_b32_e32 v31, 0xffff0000, v214
	s_nop 1
	v_fma_f32 v66, v198, v30, v66
	v_fma_f32 v67, v199, v31, v67
	v_mfma_f32_16x16x32_bf16 v[22:25], v[190:193], v[34:37], v[22:25]
	v_lshlrev_b32_e32 v30, 16, v213
	v_and_b32_e32 v31, 0xffff0000, v213
	v_fma_f32 v68, v200, v30, v68
	v_fma_f32 v69, v201, v31, v69
	v_lshlrev_b32_e32 v30, 16, v211
	v_and_b32_e32 v31, 0xffff0000, v211
	v_mfma_f32_16x16x32_bf16 v[6:9], v[194:197], v[34:37], v[6:9]
	v_fma_f32 v62, v2, v30, v62
	v_fma_f32 v63, v3, v31, v63
	v_lshlrev_b32_e32 v2, 16, v210
	v_and_b32_e32 v3, 0xffff0000, v210
	v_fma_f32 v64, v4, v2, v64
	v_fma_f32 v65, v5, v3, v65
	v_lshlrev_b32_e32 v2, 16, v212
	v_and_b32_e32 v3, 0xffff0000, v212
	v_mfma_f32_16x16x32_bf16 v[26:29], v[190:193], v[70:73], v[26:29]
	v_fma_f32 v58, v22, v2, v58
	v_fma_f32 v59, v23, v3, v59
	v_lshlrev_b32_e32 v2, 16, v174
	v_and_b32_e32 v3, 0xffff0000, v174
	v_fma_f32 v60, v24, v2, v60
	v_fma_f32 v61, v25, v3, v61
	v_lshlrev_b32_e32 v2, 16, v173
	v_and_b32_e32 v3, 0xffff0000, v173
	v_mfma_f32_16x16x32_bf16 v[10:13], v[194:197], v[70:73], v[10:13]
	v_fma_f32 v54, v6, v2, v54
	v_fma_f32 v55, v7, v3, v55
	v_lshlrev_b32_e32 v2, 16, v172
	v_and_b32_e32 v3, 0xffff0000, v172
	v_fma_f32 v56, v8, v2, v56
	v_fma_f32 v57, v9, v3, v57
	v_lshlrev_b32_e32 v2, 16, v171
	v_and_b32_e32 v3, 0xffff0000, v171
	v_mfma_f32_16x16x32_bf16 v[18:21], v[190:193], v[74:77], v[18:21]
	v_fma_f32 v50, v26, v2, v50
	v_fma_f32 v51, v27, v3, v51
	v_lshlrev_b32_e32 v2, 16, v170
	v_and_b32_e32 v3, 0xffff0000, v170
	v_fma_f32 v52, v28, v2, v52
	v_fma_f32 v53, v29, v3, v53
	v_lshlrev_b32_e32 v2, 16, v169
	v_and_b32_e32 v3, 0xffff0000, v169
	v_mfma_f32_16x16x32_bf16 v[14:17], v[194:197], v[74:77], v[14:17]
	v_fma_f32 v46, v10, v2, v46
	v_fma_f32 v47, v11, v3, v47
	v_lshlrev_b32_e32 v2, 16, v168
	v_and_b32_e32 v3, 0xffff0000, v168
	v_fma_f32 v48, v12, v2, v48
	v_fma_f32 v49, v13, v3, v49
	v_lshlrev_b32_e32 v2, 16, v165
	v_and_b32_e32 v3, 0xffff0000, v165
	v_fma_f32 v42, v18, v2, v42
	v_fma_f32 v43, v19, v3, v43
	v_lshlrev_b32_e32 v2, 16, v161
	v_and_b32_e32 v3, 0xffff0000, v161
	v_fma_f32 v44, v20, v2, v44
	v_fma_f32 v45, v21, v3, v45
	v_lshlrev_b32_e32 v2, 16, v160
	v_and_b32_e32 v3, 0xffff0000, v160
	v_fma_f32 v38, v14, v2, v38
	v_fma_f32 v39, v15, v3, v39
	v_lshlrev_b32_e32 v2, 16, v158
	v_and_b32_e32 v3, 0xffff0000, v158
	v_fma_f32 v40, v16, v2, v40
	v_fma_f32 v41, v17, v3, v41
	v_mov_b32_e32 v30, v126
	v_mov_b32_e32 v31, v127
	v_mov_b32_e32 v32, v128
	v_mov_b32_e32 v33, v129
	v_mov_b32_e32 v26, v130
	v_mov_b32_e32 v27, v131
	v_mov_b32_e32 v28, v132
	v_mov_b32_e32 v29, v133
	v_mov_b32_e32 v214, v122
	v_mov_b32_e32 v212, v116
	v_mov_b32_e32 v213, v117
	v_mov_b32_e32 v210, v114
	v_mov_b32_e32 v211, v115
	v_mov_b32_e32 v77, v186
	v_mov_b32_e32 v72, v184
	v_mov_b32_e32 v73, v183
	v_mov_b32_e32 v70, v182
	v_mov_b32_e32 v71, v181
	v_mov_b32_e32 v126, v137
	v_mov_b32_e32 v127, v139
	v_mov_b32_e32 v128, v135
	v_mov_b32_e32 v129, v140
	v_mov_b32_e32 v130, v143
	v_mov_b32_e32 v131, v142
	v_mov_b32_e32 v132, v145
	v_mov_b32_e32 v133, v147
	v_mov_b32_e32 v75, v92
	v_mov_b32_e32 v76, v93
	v_mov_b32_e32 v74, v90
	v_mov_b32_e32 v183, v84
	v_mov_b32_e32 v184, v85
	v_mov_b32_e32 v181, v82
	v_mov_b32_e32 v182, v83
	v_mov_b32_e32 v173, v164
	v_mov_b32_e32 v174, v163
	v_mov_b32_e32 v171, v162
	v_mov_b32_e32 v172, v159
	v_mov_b32_e32 v137, v134
	v_mov_b32_e32 v139, v136
	v_mov_b32_e32 v135, v138
	v_mov_b32_e32 v140, v141
	v_mov_b32_e32 v143, v144
	v_mov_b32_e32 v142, v146
	v_mov_b32_e32 v145, v148
	v_mov_b32_e32 v147, v149
	v_mov_b32_e32 v163, v100
	v_mov_b32_e32 v159, v98
	v_mov_b32_e32 v164, v99
	v_mov_b32_e32 v162, v104
	v_mov_b32_e32 v169, v157
	v_mov_b32_e32 v170, v156
	v_mov_b32_e32 v165, v155
	v_mov_b32_e32 v168, v154
	v_mov_b32_e32 v160, v153
	v_mov_b32_e32 v161, v152
	v_mov_b32_e32 v158, v150
	s_barrier
; DI unsigned pack2(float a, float b) { f2_t v = {a, b}; bf2_t r = __builtin_convertvector(v, bf2_t); return __builtin_bit_cast(unsigned, r); }
; DI int otid() { int t; asm volatile("v_mov_b32 %0, %1" : "=v"(t) : "v"((int)threadIdx.x)); __builtin_assume(t >= 0 && t < 256); return t; }
; DI void merge_tile(const Params& p, int l, int tile, char* smem) {
;     ...
;   }
;   const int lane = otid() & 63, wid = otid() >> 6, wm = wid >> 1, wn = wid & 1, fr = lane & 15, fq = lane >> 4;
; #pragma unroll
;   for (int mi = 0; mi < 4; ++mi)
;     {
;       size_t row = (size_t)mt * 128 + wm * 64 + mi * 16 + fr; int col = nt * 64 + wn * 32 + (fq & 1) * 16 + (fq >> 1) * 8;
;       uint2 a, b;
;       a.x = pack2(accM[mi][0][0], accM[mi][0][1]); a.y = pack2(accM[mi][0][2], accM[mi][0][3]);
;       b.x = pack2(accM[mi][1][0], accM[mi][1][1]); b.y = pack2(accM[mi][1][2], accM[mi][1][3]);
;       *(uint4*)(P_PROJ + row * PW + C_MERGED + col) = widen16(a, b);
;     }
	s_cbranch_scc1 .LBB0_47
	v_mov_b32 v0, v188
	v_mov_b32 v2, v188
	v_readlane_b32 s0, v255, 26
	v_lshrrev_b32_e32 v2, 1, v2
	v_and_b32_e32 v3, 15, v0
	v_and_b32_e32 v4, 64, v2
	v_or3_b32 v8, v3, v4, s27
	v_lshrrev_b32_e32 v3, 2, v0
	v_and_b32_e32 v3, 8, v3
	v_and_b32_e32 v2, 32, v2
	v_and_or_b32 v0, v0, 16, v3
	v_or3_b32 v6, v0, v2, s28
	v_mul_u32_u24_e32 v0, 0x1300, v8
	v_lshlrev_b32_e32 v0, 1, v0
	v_ashrrev_i32_e32 v7, 31, v6
	v_lshl_add_u64 v[8:9], s[58:59], 0, v[0:1]
	v_lshl_add_u64 v[6:7], v[6:7], 1, v[8:9]
	v_readlane_b32 s1, v255, 27
	v_cvt_pk_bf16_f32 v2, v66, v67
	v_cvt_pk_bf16_f32 v3, v68, v69
	v_cvt_pk_bf16_f32 v4, v62, v63
	v_cvt_pk_bf16_f32 v5, v64, v65
	v_add_co_u32_e32 v8, vcc, s16, v6
	v_permlane16_swap_b32_e32 v2, v4
	v_permlane16_swap_b32_e32 v3, v5
	v_addc_co_u32_e32 v9, vcc, 0, v7, vcc
	s_mov_b32 s1, 0x6cca000
	global_store_dwordx4 v[8:9], v[2:5], off offset:1024
	v_add_co_u32_e32 v8, vcc, s1, v6
	s_nop 0
	v_cvt_pk_bf16_f32 v2, v58, v59
	v_cvt_pk_bf16_f32 v3, v60, v61
	v_cvt_pk_bf16_f32 v4, v54, v55
	v_cvt_pk_bf16_f32 v5, v56, v57
	s_nop 0
	v_permlane16_swap_b32_e32 v2, v4
	v_permlane16_swap_b32_e32 v3, v5
	v_addc_co_u32_e32 v9, vcc, 0, v7, vcc
	s_mov_b32 s1, 0x6cf0000
	global_store_dwordx4 v[8:9], v[2:5], off offset:1024
	v_add_co_u32_e32 v8, vcc, s1, v6
	s_nop 0
	v_cvt_pk_bf16_f32 v2, v50, v51
	v_cvt_pk_bf16_f32 v3, v52, v53
	v_cvt_pk_bf16_f32 v4, v46, v47
	v_cvt_pk_bf16_f32 v5, v48, v49
	s_lshr_b32 s0, s0, 3
	v_permlane16_swap_b32_e32 v2, v4
	v_permlane16_swap_b32_e32 v3, v5
	v_addc_co_u32_e32 v9, vcc, 0, v7, vcc
	v_readlane_b32 s1, v255, 33
	global_store_dwordx4 v[8:9], v[2:5], off offset:1024
	v_add_co_u32_e32 v6, vcc, 0x6d16000, v6
	s_nop 0
	v_cvt_pk_bf16_f32 v2, v42, v43
	v_cvt_pk_bf16_f32 v3, v44, v45
	v_cvt_pk_bf16_f32 v4, v38, v39
	v_cvt_pk_bf16_f32 v5, v40, v41
	s_add_i32 s26, s26, s1
	s_add_i32 s25, s25, s0
	v_permlane16_swap_b32_e32 v2, v4
	v_permlane16_swap_b32_e32 v3, v5
	v_addc_co_u32_e32 v7, vcc, 0, v7, vcc
	s_cmpk_gt_i32 s26, 0x1ff
	global_store_dwordx4 v[6:7], v[2:5], off offset:1024
	s_cbranch_scc0 .LBB0_44
